# w_in[1]^T conversion moved from phase 3 into the wait of grid barrier 5 (split arrive / wait); its completion has its own per-XCD + global counters awaited before barrier 6; conversion workgroups leav
# speedup vs baseline: 1.0118x; 1.0021x over previous
.Lw2_pre_skip:
	s_add_i32 s0, s42, 0xffffff00
	s_cmpk_gt_i32 s76, 0xff
	s_cselect_b32 s0, s0, 0x640
	s_cmpk_gt_i32 s42, 0x1ff
	s_cselect_b32 s39, s0, s42
	s_add_u32 s6, s58, 0xa00000
	v_writelane_b32 v255, s94, 5
	s_addc_u32 s7, s59, 0
	s_add_u32 s0, s72, 0x400000
	v_writelane_b32 v255, s95, 6
	v_writelane_b32 v255, s0, 7
	s_addc_u32 s0, s73, 0
	v_writelane_b32 v255, s0, 8
	s_add_u32 s0, s58, 0x800000
	v_writelane_b32 v255, s0, 9
	s_addc_u32 s0, s59, 0
	s_add_u32 s80, s58, 0x600000
	s_addc_u32 s81, s59, 0
	s_add_u32 s70, s70, 0xc00000
	s_addc_u32 s71, s71, 0
	v_writelane_b32 v255, s70, 16
	v_writelane_b32 v255, s71, 17
	s_add_u32 s8, s58, 0x2cd1000
	s_addc_u32 s9, s59, 0
	s_add_u32 s10, s58, 0xccd1000
	s_addc_u32 s11, s59, 0
	s_add_u32 s82, s58, 0xbcd1000
	s_addc_u32 s83, s59, 0
	s_mov_b32 s84, s56
	s_mov_b32 s85, s57
	s_add_u32 s12, s58, 0xa40000
	s_addc_u32 s13, s59, 0
	s_add_u32 s28, s58, 0xc50000
	s_addc_u32 s29, s59, 0
	s_add_u32 s30, s58, 0xc90000
	s_addc_u32 s31, s59, 0
	s_add_u32 s86, s58, 0xcd0000
	s_addc_u32 s87, s59, 0
	s_add_u32 s88, s58, 0xdcd1000
	s_addc_u32 s89, s59, 0
	v_mbcnt_lo_u32_b32 v0, -1, 0
	s_add_u32 s34, s58, 0xa40060
	v_mbcnt_hi_u32_b32 v234, -1, v0
	v_bfrev_b32_e32 v0, 0.5
	v_writelane_b32 v255, s0, 10
	s_addc_u32 s35, s59, 0
	v_mov_b32_e32 v205, 0
	s_movk_i32 s90, 0x104
	s_movk_i32 s91, 0x3000
	s_movk_i32 s92, 0x1000
	s_movk_i32 s93, 0x1800
	s_movk_i32 s94, 0x2000
	s_movk_i32 s95, 0x4000
	s_mov_b32 s96, 0x9cd1000
	s_mov_b32 s97, 0xacd1000
	s_mov_b32 s33, 0xccd1000
	s_mov_b32 s74, 0xcd1000
	s_mov_b32 s75, 0xbcd1000
	s_movk_i32 s78, 0x200
	v_mov_b32_e32 v254, 0x7f800000
	v_mov_b32_e32 v232, 0x7fc00000
	v_mov_b32_e32 v233, 0xff800000
	v_lshl_or_b32 v235, v234, 2, v0
	s_mov_b32 s2, s76
	s_mov_b32 s77, s76
	s_mov_b32 s98, 0
	s_nop 0
	v_writelane_b32 v255, s98, 15
	s_cmpk_lt_i32 s76, 0x100
	s_cbranch_scc1 .Lp3_init_done
	s_addk_i32 s77, 0x300
	s_addk_i32 s2, 0x300

.LBB0_724:
	s_waitcnt vmcnt(0)
	s_barrier
	s_mov_b64 s[4:5], exec
	v_readlane_b32 s0, v255, 1
	v_readlane_b32 s1, v255, 2
	s_and_b64 s[0:1], s[4:5], s[0:1]
	s_mov_b64 exec, s[0:1]
	s_cbranch_execz .LBB0_776
	v_readlane_b32 s98, v255, 5
	v_readlane_b32 s99, v255, 6
	s_nop 3
	s_lshl_b32 s0, s3, 8
	s_add_u32 s100, s98, s0
	s_addc_u32 s101, s99, 0
	v_mov_b32_e32 v19, 0x10000
	s_waitcnt vmcnt(0) expcnt(0) lgkmcnt(0)
	ds_read_b32 v2, v19
	v_mov_b32_e32 v19, 0x10004
	ds_read_b32 v5, v19
	v_mov_b32_e32 v3, 0x1000
	v_mov_b32_e32 v4, 1
	global_atomic_add v3, v3, v4, s[100:101] offset:1024 sc0
	s_waitcnt vmcnt(0) lgkmcnt(0)
	v_add_u32_e32 v3, 1, v3
	v_mul_u32_u24_e32 v6, 4, v2
	v_add_u32_e32 v6, 1, v6
	v_cmp_eq_u32_e32 vcc, v3, v6
	s_cbranch_vccz .Lgb5_nf
	buffer_wbl2 sc1
.Lgb5_nf:
	v_mul_u32_u24_e32 v6, 5, v2
	v_cmp_eq_u32_e32 vcc, v3, v6
	s_cbranch_vccz .Lgb5_wait
	buffer_wbl2 sc1
	s_waitcnt vmcnt(0)
	v_mov_b32_e32 v3, 0x3000
	global_atomic_add v3, v3, v4, s[98:99] offset:1024 sc0
	v_readlane_b32 s0, v255, 11
	s_nop 3
	s_sub_i32 s0, 5, s0
	s_nop 0
	v_mul_lo_u32 v6, v5, s0
	s_waitcnt vmcnt(0)
	v_add_u32_e32 v3, 1, v3
	v_cmp_eq_u32_e32 vcc, v3, v6
	s_cbranch_vccz .Lgb5_wait
	v_mov_b32_e32 v3, 0x3500
	global_atomic_add v3, v4, s[98:99]
	v_mov_b32_e32 v3, 0x2400
	global_atomic_add v3, v4, s[98:99]
	v_add_u32_e32 v3, 0x100, v3
	global_atomic_add v3, v4, s[98:99]
	v_add_u32_e32 v3, 0x100, v3
	global_atomic_add v3, v4, s[98:99]
	v_add_u32_e32 v3, 0x100, v3
	global_atomic_add v3, v4, s[98:99]
	v_add_u32_e32 v3, 0x100, v3
	global_atomic_add v3, v4, s[98:99]
	v_add_u32_e32 v3, 0x100, v3
	global_atomic_add v3, v4, s[98:99]
	v_add_u32_e32 v3, 0x100, v3
	global_atomic_add v3, v4, s[98:99]
	v_add_u32_e32 v3, 0x100, v3
	global_atomic_add v3, v4, s[98:99]
	v_add_u32_e32 v3, 0x100, v3
	global_atomic_add v3, v4, s[98:99]
	v_add_u32_e32 v3, 0x100, v3
	global_atomic_add v3, v4, s[98:99]
	v_add_u32_e32 v3, 0x100, v3
	global_atomic_add v3, v4, s[98:99]
	v_add_u32_e32 v3, 0x100, v3
	global_atomic_add v3, v4, s[98:99]
	v_add_u32_e32 v3, 0x100, v3
	global_atomic_add v3, v4, s[98:99]
	v_add_u32_e32 v3, 0x100, v3
	global_atomic_add v3, v4, s[98:99]
	v_add_u32_e32 v3, 0x100, v3
	global_atomic_add v3, v4, s[98:99]
	v_add_u32_e32 v3, 0x100, v3
	global_atomic_add v3, v4, s[98:99]
.Lgb5_wait:
.LBB0_776:
	s_or_b64 exec, exec, s[4:5]
	v_readlane_b32 s8, v255, 16
	v_readlane_b32 s9, v255, 17
	s_movk_i32 s10, 0x3000
	s_movk_i32 s11, 0x104
	s_mov_b32 s37, 0
	v_mov_b32_e32 v205, 0
	s_add_i32 s7, s76, 0x100
.Lcv_loop:
	s_lshl_b32 s0, s7, 6
	s_and_b32 s6, s0, 0x3c0
	s_lshl_b32 s0, s7, 2
	s_and_b32 s0, s0, 0xfc0
	s_add_i32 s36, s0, 0xfffffc00
	v_mov_b32_e32 v8, v207
	s_lshl_b64 s[0:1], s[36:37], 2
	s_add_u32 s0, s8, s0
	v_lshlrev_b32_e32 v0, 4, v8
	v_ashrrev_i32_e32 v6, 4, v8
	s_addc_u32 s1, s9, s1
	v_and_b32_e32 v204, 0xf0, v0
	v_lshl_add_u64 v[4:5], s[0:1], 0, v[204:205]
	v_add_u32_e32 v9, s6, v6
	v_mad_i64_i32 v[0:1], s[0:1], v9, s10, v[4:5]
	global_load_dwordx4 v[0:3], v[0:1], off nt
	v_mad_u64_u32 v[6:7], s[0:1], v6, s11, v[204:205]
	v_add_u32_e32 v7, 0x1040, v6
	v_ashrrev_i32_e32 v22, 3, v8
	s_waitcnt vmcnt(0)
	ds_write2_b32 v6, v0, v1 offset1:1
	ds_write2_b32 v6, v2, v3 offset0:2 offset1:3
	v_add_u32_e32 v0, 16, v9
	v_mad_i64_i32 v[0:1], s[0:1], v0, s10, v[4:5]
	global_load_dwordx4 v[0:3], v[0:1], off nt
	s_waitcnt vmcnt(0)
	ds_write2_b32 v7, v0, v1 offset1:1
	v_add_u32_e32 v0, 0x1048, v6
	ds_write2_b32 v0, v2, v3 offset1:1
	v_add_u32_e32 v0, 32, v9
	v_mad_i64_i32 v[0:1], s[0:1], v0, s10, v[4:5]
	global_load_dwordx4 v[0:3], v[0:1], off nt
	v_add_u32_e32 v7, 0x2080, v6
	s_waitcnt vmcnt(0)
	ds_write2_b32 v7, v0, v1 offset1:1
	v_add_u32_e32 v0, 0x2088, v6
	ds_write2_b32 v0, v2, v3 offset1:1
	v_add_u32_e32 v0, 48, v9
	v_mad_i64_i32 v[0:1], s[0:1], v0, s10, v[4:5]
	global_load_dwordx4 v[0:3], v[0:1], off nt
	v_add_u32_e32 v4, 0x30c0, v6
	s_lshl_b32 s0, s6, 1
	s_add_u32 s0, s58, s0
	s_addc_u32 s1, s59, 0
	s_waitcnt vmcnt(0)
	ds_write2_b32 v4, v0, v1 offset1:1
	v_add_u32_e32 v0, 0x30c8, v6
	ds_write2_b32 v0, v2, v3 offset1:1
	v_lshlrev_b32_e32 v0, 3, v8
	v_and_b32_e32 v0, 56, v0
	v_lshlrev_b32_e32 v204, 1, v0
	v_mul_u32_u24_e32 v0, 0x104, v0
	v_lshl_add_u32 v0, v22, 2, v0
	s_waitcnt lgkmcnt(0)
	s_barrier
	ds_read2_b32 v[6:7], v0 offset1:32
	ds_read2_b32 v[8:9], v0 offset0:65 offset1:97
	ds_read2_b32 v[10:11], v0 offset0:130 offset1:162
	ds_read2_b32 v[12:13], v0 offset0:195 offset1:227
	v_add_u32_e32 v0, 0x400, v0
	ds_read2_b32 v[14:15], v0 offset0:4 offset1:36
	ds_read2_b32 v[16:17], v0 offset0:69 offset1:101
	ds_read2_b32 v[18:19], v0 offset0:134 offset1:166
	ds_read2_b32 v[20:21], v0 offset0:199 offset1:231
	v_add_u32_e32 v22, s36, v22
	v_ashrrev_i32_e32 v23, 31, v22
	v_lshl_add_u64 v[4:5], s[0:1], 0, v[204:205]
	v_lshlrev_b64 v[24:25], 11, v[22:23]
	s_waitcnt lgkmcnt(6)
	v_cvt_pk_bf16_f32 v0, v6, v8
	s_waitcnt lgkmcnt(4)
	v_cvt_pk_bf16_f32 v1, v10, v12
	s_waitcnt lgkmcnt(2)
	v_cvt_pk_bf16_f32 v2, v14, v16
	s_waitcnt lgkmcnt(0)
	v_cvt_pk_bf16_f32 v3, v18, v20
	v_lshl_add_u64 v[24:25], v[4:5], 0, v[24:25]
	v_add_u32_e32 v6, 32, v22
	global_store_dwordx4 v[24:25], v[0:3], off
	s_nop 1
	v_cvt_pk_bf16_f32 v0, v7, v9
	v_ashrrev_i32_e32 v7, 31, v6
	v_lshlrev_b64 v[6:7], 11, v[6:7]
	v_cvt_pk_bf16_f32 v1, v11, v13
	v_cvt_pk_bf16_f32 v2, v15, v17
	v_cvt_pk_bf16_f32 v3, v19, v21
	v_lshl_add_u64 v[4:5], v[4:5], 0, v[6:7]
	global_store_dwordx4 v[4:5], v[0:3], off
	s_barrier
	s_addk_i32 s7, 0x200
	s_cmpk_lt_i32 s7, 0x400
	s_cbranch_scc1 .Lcv_loop
	s_waitcnt vmcnt(0)
	s_barrier
	s_mov_b64 s[12:13], exec
	v_readlane_b32 s0, v255, 1
	v_readlane_b32 s1, v255, 2
	s_nop 1
	s_mov_b64 exec, s[0:1]
	s_cbranch_execz .Lthr0_b5
	v_readlane_b32 s98, v255, 5
	v_readlane_b32 s99, v255, 6
	v_mov_b32_e32 v19, 0x10000
	ds_read_b32 v2, v19
	s_lshl_b32 s0, s3, 3
	s_add_i32 s0, s0, 0x380
	v_mov_b32_e32 v3, s0
	v_mov_b32_e32 v4, 1
	s_nop 2
	global_atomic_add v3, v3, v4, s[98:99] sc0
	s_waitcnt vmcnt(0) lgkmcnt(0)
	v_add_u32_e32 v3, 1, v3
	v_cmp_eq_u32_e32 vcc, v3, v2
	s_cbranch_vccz .Lcv_sig_done
	buffer_wbl2 sc1
	s_waitcnt vmcnt(0)
	v_mov_b32_e32 v3, 0x3c0
	global_atomic_add v3, v4, s[98:99]
.Lcv_sig_done:
	v_readlane_b32 s98, v255, 5
	v_readlane_b32 s99, v255, 6
	s_nop 3
	s_lshl_b32 s0, s3, 8
	s_add_u32 s100, s98, s0
	s_addc_u32 s101, s99, 0
	s_nop 2
	v_mov_b32_e32 v3, 0x2000
	v_mov_b32_e32 v20, 0
.Lgb5_loop:
	global_load_dword v21, v3, s[100:101] offset:1024 sc1
	s_waitcnt vmcnt(0)
	v_cmp_le_u32_e32 vcc, 5, v21
	s_cbranch_vccnz .Lgb5_done
	s_sleep 1
	v_add_u32_e32 v20, 1, v20
	v_cmp_gt_u32_e32 vcc, 0x8000, v20
	s_cbranch_vccnz .Lgb5_loop

.Lthr0_b5:
	s_mov_b64 exec, s[12:13]
	s_barrier
	s_and_b64 vcc, exec, s[38:39]
	s_waitcnt lgkmcnt(0)
	s_barrier
	s_cbranch_vccnz .LBB0_783
	s_cmpk_gt_i32 s76, 0x1ff
	s_cbranch_scc1 .LBB0_782
	s_add_u32 s4, s58, 0xcd1000
	s_addc_u32 s5, s59, 0
	s_add_u32 s6, s58, 0x600000
	s_addc_u32 s7, s59, 0
	s_add_u32 s8, s58, 0xb0d1000
	s_addc_u32 s9, s59, 0
	s_movk_i32 s2, 0x70
	v_mov_b32_e32 v129, 0
	s_mov_b32 s16, 0x10000
	s_mov_b32 s11, 0
	s_mov_b32 s17, 0x20000
	s_mov_b32 s18, 0x30000
	s_mov_b32 s19, 0x40000
	s_mov_b32 s20, 0x50000
	s_mov_b32 s21, 0x60000
	s_mov_b32 s22, 0x70000
	s_mov_b64 s[12:13], 0xfd13000
	s_mov_b32 s23, 0xfd13000
	s_mov_b32 s24, s76

.LBB0_789:
	s_mov_b64 s[12:13], exec
	v_readlane_b32 s0, v255, 1
	v_readlane_b32 s1, v255, 2
	s_nop 1
	s_mov_b64 exec, s[0:1]
	s_cbranch_execz .Lthr0_cvw
	v_readlane_b32 s98, v255, 5
	v_readlane_b32 s99, v255, 6
	v_mov_b32_e32 v19, 0x10004
	ds_read_b32 v5, v19
	v_mov_b32_e32 v3, 0x3c0
	v_mov_b32_e32 v20, 0
	s_waitcnt lgkmcnt(0)
	s_nop 2
.Lcvw_loop:
	global_load_dword v21, v3, s[98:99] sc1
	s_waitcnt vmcnt(0)
	v_cmp_ge_u32_e32 vcc, v21, v5
	s_cbranch_vccnz .Lcvw_done
	s_sleep 1
	v_add_u32_e32 v20, 1, v20
	v_cmp_gt_u32_e32 vcc, 0x8000, v20
	s_cbranch_vccnz .Lcvw_loop

.Lthr0_cvw:
	s_mov_b64 exec, s[12:13]
	s_barrier
	s_waitcnt vmcnt(0)
	s_barrier
	s_mov_b64 s[4:5], exec
	v_readlane_b32 s0, v255, 1
	v_readlane_b32 s1, v255, 2
	s_and_b64 s[0:1], s[4:5], s[0:1]
	s_mov_b64 exec, s[0:1]
	s_cbranch_execz .LBB0_841
	v_mov_b32_e32 v0, 0x10000
	s_waitcnt vmcnt(0) expcnt(0) lgkmcnt(0)
	ds_read_b32 v2, v0
	v_mov_b32_e32 v0, 0x10004
	ds_read_b32 v0, v0
	s_waitcnt lgkmcnt(1)
	v_cmp_ne_u32_e32 vcc, 0, v2
	s_cbranch_vccnz .LBB0_805
	s_add_u32 s6, s58, 0xfd29200
	s_addc_u32 s7, s59, 0
	s_add_u32 s8, s58, 0xfd29400
	s_addc_u32 s9, s59, 0
	s_add_u32 s10, s58, 0xfd29500
	s_addc_u32 s11, s59, 0
	s_add_u32 s12, s58, 0xfd29600
	s_addc_u32 s13, s59, 0
	s_add_u32 s14, s58, 0xfd29700
	s_addc_u32 s15, s59, 0
	s_add_u32 s16, s58, 0xfd29800
	s_addc_u32 s17, s59, 0
	s_add_u32 s18, s58, 0xfd29900
	s_addc_u32 s19, s59, 0
	s_add_u32 s20, s58, 0xfd29a00
	s_addc_u32 s21, s59, 0
	s_add_u32 s22, s58, 0xfd29b00
	s_addc_u32 s23, s59, 0
	s_add_u32 s24, s58, 0xfd29c00
	s_addc_u32 s25, s59, 0
	s_add_u32 s26, s58, 0xfd29d00
	s_addc_u32 s27, s59, 0
	s_add_u32 s28, s58, 0xfd29e00
	s_addc_u32 s29, s59, 0
	s_add_u32 s30, s58, 0xfd29f00
	s_addc_u32 s31, s59, 0
	s_add_u32 s34, s58, 0xfd2a000
	s_addc_u32 s35, s59, 0
	s_add_u32 s36, s58, 0xfd2a100
	s_addc_u32 s37, s59, 0
	s_add_u32 s40, s58, 0xfd2a200
	v_readlane_b32 s0, v255, 0
	s_addc_u32 s41, s59, 0
	s_mul_i32 s2, s43, s0
	s_add_u32 s44, s58, 0xfd2a300
	s_mul_i32 s2, s2, s42
	s_addc_u32 s45, s59, 0
	s_mov_b32 s33, 1
	v_mov_b32_e32 v16, 0
	s_branch .LBB0_793
